# FF1 and FF2 GEMM k-loops both software-pipelined across the barrier (generic patch; in_proj/out_proj left as baseline)
# baseline (speedup 1.0000x reference)
; #define ROW4(accv, r, av)                                                                              \
;     accv[r][0] = MFMA16(av, b0, accv[r][0]); accv[r][1] = MFMA16(av, b1, accv[r][1]);                      \
;     accv[r][2] = MFMA16(av, b2, accv[r][2]); accv[r][3] = MFMA16(av, b3, accv[r][3]);
; template <int EPI>
; __device__ __forceinline__ void gemm_tile_dma(const bft* __restrict__ A, int lda, const bft* __restrict__ Bt, int K, int row0, int col0,
;                                               char* smem, const EpiArgs& e) {
;     ...
;   for (int kt = 0; kt < nk; ++kt) {
;     if (kt + 2 < nk) asm volatile("s_waitcnt vmcnt(8)" ::: "memory");
;     else if (kt + 1 < nk) asm volatile("s_waitcnt vmcnt(4)" ::: "memory");
;     else asm volatile("s_waitcnt vmcnt(0)" ::: "memory");
;     __builtin_amdgcn_s_barrier();
;     asm volatile("" ::: "memory");
;     const bool pf = kt + 3 < nk;
;     const unsigned so = (unsigned)(kt & 3) * GST;
;     bf16x8 a0, a1, a2, a3, b0, b1, b2, b3;
;     asm volatile(
;         "ds_read_b128 %0, %8\n\t"
;         "ds_read_b128 %1, %8 offset:1024\n\t"
;         "ds_read_b128 %2, %8 offset:2048\n\t"
;         "ds_read_b128 %3, %8 offset:3072\n\t"
;         "ds_read_b128 %4, %9\n\t"
;         "ds_read_b128 %5, %9 offset:1024\n\t"
;         "ds_read_b128 %6, %9 offset:2048\n\t"
;         "ds_read_b128 %7, %9 offset:3072\n\t"
;         "s_waitcnt lgkmcnt(0)"
;         : "=&v"(a0), "=&v"(a1), "=&v"(a2), "=&v"(a3), "=&v"(b0), "=&v"(b1), "=&v"(b2), "=&v"(b3)
;         : "v"(lds_a + so), "v"(lds_b + so)
;         : "memory");
;     ...
;     ROW4(accL, 0, a0) ROW4(accL, 1, a1)
;     if (pf) GEMM_DMA_A(kt + 3)
;     ROW4(accL, 2, a2) ROW4(accL, 3, a3)
;     asm volatile(
;         "ds_read_b128 %0, %4 offset:4096\n\t"
;         "ds_read_b128 %1, %4 offset:5120\n\t"
;         "ds_read_b128 %2, %4 offset:6144\n\t"
;         "ds_read_b128 %3, %4 offset:7168\n\t"
;         "s_waitcnt lgkmcnt(0)"
;         : "=&v"(a0), "=&v"(a1), "=&v"(a2), "=&v"(a3)
;         : "v"(lds_a + so)
;         : "memory");
;     ROW4(accH, 0, a0) ROW4(accH, 1, a1)
;     if (pf) GEMM_DMA_B(kt + 3)
;     ROW4(accH, 2, a2) ROW4(accH, 3, a3)
;     ...
;   }
.LBB0_1312:
	s_and_b32 s27, s17, 0x18000
	v_add_u32_e32 v158, s27, v132
	ds_read_b128 v[172:175], v158 offset:4096
	ds_read_b128 v[176:179], v158 offset:5120
	ds_read_b128 v[188:191], v158 offset:6144
	ds_read_b128 v[192:195], v158 offset:7168
	v_or_b32_e32 v159, s27, v133
	s_add_i32 s27, s17, 0x18000
	s_and_b32 s27, s27, 0x18000
	s_waitcnt lgkmcnt(4)
	v_add_u32_e32 v159, s27, v184
	v_mfma_f32_16x16x32_bf16 v[124:127], v[134:137], v[150:153], v[124:127]
	v_readfirstlane_b32 s27, v159
	s_mov_b32 m0, s27
	s_mov_b64 s[38:39], 0x3bf800c0
	v_mfma_f32_16x16x32_bf16 v[120:123], v[134:137], v[154:157], v[120:123]
	v_mfma_f32_16x16x32_bf16 v[116:119], v[134:137], v[162:165], v[116:119]
	v_mfma_f32_16x16x32_bf16 v[108:111], v[134:137], v[166:169], v[108:111]
	v_lshl_add_u64 v[134:135], v[130:131], 0, s[12:13]
	v_lshl_add_u64 v[136:137], v[134:135], 0, s[28:29]
	v_lshl_add_u64 v[134:135], v[134:135], 0, s[20:21]
	v_mfma_f32_16x16x32_bf16 v[104:107], v[138:141], v[150:153], v[104:107]
	global_load_lds_dwordx4 v[136:137], off
	v_mfma_f32_16x16x32_bf16 v[100:103], v[138:141], v[154:157], v[100:103]
	v_mfma_f32_16x16x32_bf16 v[96:99], v[138:141], v[162:165], v[96:99]
	v_mfma_f32_16x16x32_bf16 v[92:95], v[138:141], v[166:169], v[92:95]
	v_add_u32_e32 v138, 0x2000, v159
	s_nop 0
	v_readfirstlane_b32 s34, v138
	s_mov_b32 m0, s34
	v_mfma_f32_16x16x32_bf16 v[88:91], v[142:145], v[150:153], v[88:91]
	global_load_lds_dwordx4 v[134:135], off
	v_mfma_f32_16x16x32_bf16 v[84:87], v[142:145], v[154:157], v[84:87]
	v_mfma_f32_16x16x32_bf16 v[80:83], v[142:145], v[162:165], v[80:83]
	v_mfma_f32_16x16x32_bf16 v[76:79], v[142:145], v[166:169], v[76:79]
	v_mfma_f32_16x16x32_bf16 v[72:75], v[146:149], v[150:153], v[72:75]
	v_mfma_f32_16x16x32_bf16 v[68:71], v[146:149], v[154:157], v[68:71]
	v_mfma_f32_16x16x32_bf16 v[64:67], v[146:149], v[162:165], v[64:67]
	v_mfma_f32_16x16x32_bf16 v[60:63], v[146:149], v[166:169], v[60:63]
	s_waitcnt lgkmcnt(0)
	s_waitcnt vmcnt(6)
	s_barrier
	s_add_i32 s32, s17, 0x8000
	s_and_b32 s32, s32, 0x18000
	v_add_u32_e32 v160, s32, v132
	v_or_b32_e32 v170, s32, v133
	ds_read_b128 v[200:203], v160
	ds_read_b128 v[204:207], v160 offset:1024
	ds_read_b128 v[208:211], v160 offset:2048
	ds_read_b128 v[212:215], v160 offset:3072
	ds_read_b128 v[216:219], v170
	ds_read_b128 v[220:223], v170 offset:1024
	ds_read_b128 v[224:227], v170 offset:2048
	ds_read_b128 v[228:231], v170 offset:3072
	s_nop 0
	v_mfma_f32_16x16x32_bf16 v[52:55], v[176:179], v[150:153], v[52:55]
	v_mfma_f32_16x16x32_bf16 v[12:15], v[176:179], v[154:157], v[12:15]
	v_mfma_f32_16x16x32_bf16 v[48:51], v[176:179], v[162:165], v[48:51]
	v_mfma_f32_16x16x32_bf16 v[16:19], v[176:179], v[166:169], v[16:19]
	v_add_u32_e32 v138, 0x4000, v159
	v_add_u32_e32 v139, 0x6000, v159
	v_readfirstlane_b32 s27, v138
	v_mfma_f32_16x16x32_bf16 v[112:115], v[172:175], v[150:153], v[112:115]
	v_readfirstlane_b32 s34, v139
	s_mov_b32 m0, s27
	v_mfma_f32_16x16x32_bf16 v[4:7], v[172:175], v[154:157], v[4:7]
	v_mfma_f32_16x16x32_bf16 v[56:59], v[172:175], v[162:165], v[56:59]
	v_mfma_f32_16x16x32_bf16 v[8:11], v[172:175], v[166:169], v[8:11]
	v_lshl_add_u64 v[134:135], v[128:129], 0, s[12:13]
	v_lshl_add_u64 v[136:137], v[134:135], 0, s[38:39]
	s_mov_b64 s[38:39], 0x3bfc00c0
	v_lshl_add_u64 v[134:135], v[134:135], 0, s[38:39]
	global_load_lds_dwordx4 v[136:137], off
	s_mov_b32 m0, s34
	v_mfma_f32_16x16x32_bf16 v[44:47], v[188:191], v[150:153], v[44:47]
	global_load_lds_dwordx4 v[134:135], off
	s_add_u32 s12, s12, 64
	v_mfma_f32_16x16x32_bf16 v[20:23], v[188:191], v[154:157], v[20:23]
	s_addc_u32 s13, s13, 0
	s_add_i32 s17, s17, 0x8000
	s_cmpk_eq_i32 s12, 0x740
	v_mfma_f32_16x16x32_bf16 v[40:43], v[188:191], v[162:165], v[40:43]
	v_mfma_f32_16x16x32_bf16 v[24:27], v[188:191], v[166:169], v[24:27]
	v_mfma_f32_16x16x32_bf16 v[36:39], v[192:195], v[150:153], v[36:39]
	v_mfma_f32_16x16x32_bf16 v[28:31], v[192:195], v[154:157], v[28:31]
	v_mfma_f32_16x16x32_bf16 v[32:35], v[192:195], v[162:165], v[32:35]
	v_mfma_f32_16x16x32_bf16 v[0:3], v[192:195], v[166:169], v[0:3]
	s_waitcnt lgkmcnt(0)
	v_mov_b64_e32 v[134:135], v[200:201]
	v_mov_b64_e32 v[136:137], v[202:203]
	v_mov_b64_e32 v[138:139], v[204:205]
	v_mov_b64_e32 v[140:141], v[206:207]
	v_mov_b64_e32 v[142:143], v[208:209]
	v_mov_b64_e32 v[144:145], v[210:211]
	v_mov_b64_e32 v[146:147], v[212:213]
	v_mov_b64_e32 v[148:149], v[214:215]
	v_mov_b64_e32 v[150:151], v[216:217]
	v_mov_b64_e32 v[152:153], v[218:219]
	v_mov_b64_e32 v[154:155], v[220:221]
	v_mov_b64_e32 v[156:157], v[222:223]
	v_mov_b64_e32 v[162:163], v[224:225]
	v_mov_b64_e32 v[164:165], v[226:227]
	v_mov_b64_e32 v[166:167], v[228:229]
	v_mov_b64_e32 v[168:169], v[230:231]
	s_cbranch_scc0 .LBB0_1312
	s_waitcnt vmcnt(8)
	s_barrier
; #define ROW4(accv, r, av)                                                                              \
;     accv[r][0] = MFMA16(av, b0, accv[r][0]); accv[r][1] = MFMA16(av, b1, accv[r][1]);                      \
;     accv[r][2] = MFMA16(av, b2, accv[r][2]); accv[r][3] = MFMA16(av, b3, accv[r][3]);
; template <int EPI>
; __device__ __forceinline__ void gemm_tile_dma(const bft* __restrict__ A, int lda, const bft* __restrict__ Bt, int K, int row0, int col0,
;                                               char* smem, const EpiArgs& e) {
;     ...
;   for (int kt = 0; kt < nk; ++kt) {
;     if (kt + 2 < nk) asm volatile("s_waitcnt vmcnt(8)" ::: "memory");
;     else if (kt + 1 < nk) asm volatile("s_waitcnt vmcnt(4)" ::: "memory");
;     else asm volatile("s_waitcnt vmcnt(0)" ::: "memory");
;     __builtin_amdgcn_s_barrier();
;     asm volatile("" ::: "memory");
;     const bool pf = kt + 3 < nk;
;     const unsigned so = (unsigned)(kt & 3) * GST;
;     bf16x8 a0, a1, a2, a3, b0, b1, b2, b3;
;     asm volatile(
;         "ds_read_b128 %0, %8\n\t"
;         "ds_read_b128 %1, %8 offset:1024\n\t"
;         "ds_read_b128 %2, %8 offset:2048\n\t"
;         "ds_read_b128 %3, %8 offset:3072\n\t"
;         "ds_read_b128 %4, %9\n\t"
;         "ds_read_b128 %5, %9 offset:1024\n\t"
;         "ds_read_b128 %6, %9 offset:2048\n\t"
;         "ds_read_b128 %7, %9 offset:3072\n\t"
;         "s_waitcnt lgkmcnt(0)"
;         : "=&v"(a0), "=&v"(a1), "=&v"(a2), "=&v"(a3), "=&v"(b0), "=&v"(b1), "=&v"(b2), "=&v"(b3)
;         : "v"(lds_a + so), "v"(lds_b + so)
;         : "memory");
;     ...
;     ROW4(accL, 0, a0) ROW4(accL, 1, a1)
;     if (pf) GEMM_DMA_A(kt + 3)
;     ROW4(accL, 2, a2) ROW4(accL, 3, a3)
;     asm volatile(
;         "ds_read_b128 %0, %4 offset:4096\n\t"
;         "ds_read_b128 %1, %4 offset:5120\n\t"
;         "ds_read_b128 %2, %4 offset:6144\n\t"
;         "ds_read_b128 %3, %4 offset:7168\n\t"
;         "s_waitcnt lgkmcnt(0)"
;         : "=&v"(a0), "=&v"(a1), "=&v"(a2), "=&v"(a3)
;         : "v"(lds_a + so)
;         : "memory");
;     ROW4(accH, 0, a0) ROW4(accH, 1, a1)
;     if (pf) GEMM_DMA_B(kt + 3)
;     ROW4(accH, 2, a2) ROW4(accH, 3, a3)
;     ...
;   }
	v_add_u32_e32 v158, 0x8000, v132
	v_or_b32_e32 v159, 0x8000, v133
	ds_read_b128 v[128:131], v158
	ds_read_b128 v[134:137], v158 offset:1024
	ds_read_b128 v[138:141], v158 offset:2048
	ds_read_b128 v[142:145], v158 offset:3072
	ds_read_b128 v[146:149], v159
	ds_read_b128 v[150:153], v159 offset:1024
	ds_read_b128 v[154:157], v159 offset:2048
	ds_read_b128 v[162:165], v159 offset:3072
	s_waitcnt lgkmcnt(0)
	v_or_b32_e32 v159, 0x10000, v133
	v_mfma_f32_16x16x32_bf16 v[124:127], v[128:131], v[146:149], v[124:127]
	v_add_u32_e32 v178, 0x18000, v132
	v_and_b32_e32 v160, 63, v182
	v_lshrrev_b32_e32 v179, 6, v182
	v_mfma_f32_16x16x32_bf16 v[120:123], v[128:131], v[150:153], v[120:123]
	s_movk_i32 s12, 0x4400
	v_mfma_f32_16x16x32_bf16 v[116:119], v[128:131], v[154:157], v[116:119]
	v_mfma_f32_16x16x32_bf16 v[108:111], v[128:131], v[162:165], v[108:111]
	v_mfma_f32_16x16x32_bf16 v[104:107], v[134:137], v[146:149], v[104:107]
	v_mfma_f32_16x16x32_bf16 v[100:103], v[134:137], v[150:153], v[100:103]
	v_mfma_f32_16x16x32_bf16 v[96:99], v[134:137], v[154:157], v[96:99]
	v_mfma_f32_16x16x32_bf16 v[88:91], v[138:141], v[146:149], v[88:91]
	v_mfma_f32_16x16x32_bf16 v[84:87], v[138:141], v[150:153], v[84:87]
	v_mfma_f32_16x16x32_bf16 v[80:83], v[138:141], v[154:157], v[80:83]
	v_mfma_f32_16x16x32_bf16 v[76:79], v[138:141], v[162:165], v[76:79]
	v_mfma_f32_16x16x32_bf16 v[92:95], v[134:137], v[162:165], v[92:95]
	v_mfma_f32_16x16x32_bf16 v[72:75], v[142:145], v[146:149], v[72:75]
	v_mfma_f32_16x16x32_bf16 v[68:71], v[142:145], v[150:153], v[68:71]
	v_mfma_f32_16x16x32_bf16 v[64:67], v[142:145], v[154:157], v[64:67]
	v_mfma_f32_16x16x32_bf16 v[60:63], v[142:145], v[162:165], v[60:63]
	ds_read_b128 v[128:131], v158 offset:4096
	ds_read_b128 v[134:137], v158 offset:5120
	ds_read_b128 v[138:141], v158 offset:6144
	ds_read_b128 v[142:145], v158 offset:7168
	s_waitcnt lgkmcnt(0)
	s_waitcnt vmcnt(4)
	s_barrier
	v_mfma_f32_16x16x32_bf16 v[112:115], v[128:131], v[146:149], v[112:115]
	v_add_u32_e32 v158, 0x10000, v132
	v_mfma_f32_16x16x32_bf16 v[4:7], v[128:131], v[150:153], v[4:7]
	v_mfma_f32_16x16x32_bf16 v[166:169], v[128:131], v[154:157], v[56:59]
	v_mfma_f32_16x16x32_bf16 v[8:11], v[128:131], v[162:165], v[8:11]
	v_mfma_f32_16x16x32_bf16 v[52:55], v[134:137], v[146:149], v[52:55]
	v_mfma_f32_16x16x32_bf16 v[12:15], v[134:137], v[150:153], v[12:15]
	v_mfma_f32_16x16x32_bf16 v[48:51], v[134:137], v[154:157], v[48:51]
	v_mfma_f32_16x16x32_bf16 v[16:19], v[134:137], v[162:165], v[16:19]
	v_mfma_f32_16x16x32_bf16 v[128:131], v[138:141], v[146:149], v[44:47]
	v_mfma_f32_16x16x32_bf16 v[20:23], v[138:141], v[150:153], v[20:23]
	v_mfma_f32_16x16x32_bf16 v[134:137], v[138:141], v[154:157], v[40:43]
	v_mfma_f32_16x16x32_bf16 v[24:27], v[138:141], v[162:165], v[24:27]
	v_mfma_f32_16x16x32_bf16 v[36:39], v[142:145], v[146:149], v[36:39]
	v_mfma_f32_16x16x32_bf16 v[28:31], v[142:145], v[150:153], v[28:31]
	v_mfma_f32_16x16x32_bf16 v[138:141], v[142:145], v[154:157], v[32:35]
	v_mfma_f32_16x16x32_bf16 v[32:35], v[142:145], v[162:165], v[0:3]
	ds_read_b128 v[0:3], v158
	ds_read_b128 v[56:59], v158 offset:1024
	ds_read_b128 v[142:145], v158 offset:2048
	ds_read_b128 v[146:149], v158 offset:3072
	ds_read_b128 v[150:153], v159
	ds_read_b128 v[44:47], v159 offset:1024
	ds_read_b128 v[154:157], v159 offset:2048
	ds_read_b128 v[40:43], v159 offset:3072
	s_waitcnt lgkmcnt(0)
	s_nop 0
	v_mfma_f32_16x16x32_bf16 v[124:127], v[0:3], v[150:153], v[124:127]
	v_mfma_f32_16x16x32_bf16 v[120:123], v[0:3], v[44:47], v[120:123]
	v_mfma_f32_16x16x32_bf16 v[116:119], v[0:3], v[154:157], v[116:119]
	v_mfma_f32_16x16x32_bf16 v[0:3], v[0:3], v[40:43], v[108:111]
	v_mfma_f32_16x16x32_bf16 v[104:107], v[56:59], v[150:153], v[104:107]
	v_mfma_f32_16x16x32_bf16 v[108:111], v[56:59], v[44:47], v[100:103]
	v_mfma_f32_16x16x32_bf16 v[96:99], v[56:59], v[154:157], v[96:99]
	v_mfma_f32_16x16x32_bf16 v[186:189], v[142:145], v[150:153], v[88:91]
	v_mfma_f32_16x16x32_bf16 v[190:193], v[142:145], v[44:47], v[84:87]
	v_mfma_f32_16x16x32_bf16 v[210:213], v[142:145], v[154:157], v[80:83]
	v_mfma_f32_16x16x32_bf16 v[214:217], v[142:145], v[40:43], v[76:79]
	v_mfma_f32_16x16x32_bf16 v[92:95], v[56:59], v[40:43], v[92:95]
	v_mfma_f32_16x16x32_bf16 v[226:229], v[146:149], v[154:157], v[64:67]
	ds_read_b128 v[84:87], v158 offset:4096
	ds_read_b128 v[76:79], v158 offset:5120
	ds_read_b128 v[64:67], v158 offset:6144
	ds_read_b128 v[56:59], v158 offset:7168
	s_waitcnt lgkmcnt(0)
	s_waitcnt vmcnt(0)
	s_barrier
	v_mfma_f32_16x16x32_bf16 v[218:221], v[146:149], v[150:153], v[72:75]
	v_mfma_f32_16x16x32_bf16 v[222:225], v[146:149], v[44:47], v[68:71]
	v_mfma_f32_16x16x32_bf16 v[230:233], v[146:149], v[40:43], v[60:63]
	v_mfma_f32_16x16x32_bf16 v[234:237], v[84:87], v[150:153], v[112:115]
	v_mfma_f32_16x16x32_bf16 v[238:241], v[76:79], v[150:153], v[52:55]
	v_mfma_f32_16x16x32_bf16 v[68:71], v[76:79], v[154:157], v[48:51]
	v_mfma_f32_16x16x32_bf16 v[242:245], v[64:67], v[150:153], v[128:131]
	v_mfma_f32_16x16x32_bf16 v[246:249], v[56:59], v[150:153], v[36:39]
	s_nop 1
	v_or_b32_e32 v128, 0x18000, v133
	ds_read_b128 v[36:39], v178
	ds_read_b128 v[48:51], v178 offset:1024
	ds_read_b128 v[112:115], v178 offset:2048
	ds_read_b128 v[198:201], v178 offset:3072
	ds_read_b128 v[206:209], v128
	ds_read_b128 v[88:91], v128 offset:1024
	ds_read_b128 v[100:103], v128 offset:2048
	ds_read_b128 v[52:55], v128 offset:3072
	s_waitcnt lgkmcnt(0)
	v_mfma_f32_16x16x32_bf16 v[60:63], v[84:87], v[154:157], v[166:169]
	v_mfma_f32_16x16x32_bf16 v[72:75], v[64:67], v[154:157], v[134:137]
	v_mfma_f32_16x16x32_bf16 v[80:83], v[56:59], v[154:157], v[138:141]
	v_mfma_f32_16x16x32_bf16 v[162:165], v[48:51], v[206:209], v[104:107]
	v_mfma_f32_16x16x32_bf16 v[156:159], v[48:51], v[88:91], v[108:111]
	v_mfma_f32_16x16x32_bf16 v[152:155], v[48:51], v[100:103], v[96:99]
	v_mfma_f32_16x16x32_bf16 v[144:147], v[112:115], v[206:209], v[186:189]
	v_mfma_f32_16x16x32_bf16 v[140:143], v[112:115], v[88:91], v[190:193]
	s_nop 1
	v_mul_lo_u32 v189, v179, s12
	s_mov_b32 s12, 0
	v_mfma_f32_16x16x32_bf16 v[136:139], v[112:115], v[100:103], v[210:213]
	v_bfe_u32 v191, v182, 2, 4
	v_and_b32_e32 v195, 12, v191
	v_mul_u32_u24_e32 v187, 0x110, v195
	v_mfma_f32_16x16x32_bf16 v[132:135], v[112:115], v[52:55], v[214:217]
	ds_read_b128 v[112:115], v178 offset:4096
	ds_read_b128 v[108:111], v178 offset:5120
	ds_read_b128 v[104:107], v178 offset:6144
	ds_read_b128 v[96:99], v178 offset:7168
	s_waitcnt lgkmcnt(0)
	v_and_b32_e32 v178, 0xc0, v182
	v_or_b32_e32 v190, s16, v178
	v_mfma_f32_16x16x32_bf16 v[202:205], v[36:39], v[206:209], v[124:127]
	s_waitcnt vmcnt(0) lgkmcnt(0)
	s_barrier
; template <int EPI>
; DI void epilogue_tile(const EpiArgs& e, int row0, int wrow, int wcol, f32x4 (&acc)[4][4], char* smem, const float* rsm, int wave, int lane,
;                       bool final_sync = true) {
;     ...
;       if constexpr (EPI == EPI_FF1) {
;         const float bb = e.bias[col];
; #pragma unroll
;         for (int j = 0; j < 4; ++j) { const float t = fmaxf(v[j] + bb, 0.f); v[j] = t * t; }
;       }
;       if (transposed) {
;         *(f32x4*)(stage + lcol * STG + lrow) = (f32x4){v[0], v[1], v[2], v[3]};
;       } else {
; #pragma unroll
;         for (int j = 0; j < 4; ++j) stage[(lrow + j) * STG + lcol] = v[j];
	v_mfma_f32_16x16x32_bf16 v[174:177], v[36:39], v[88:91], v[120:123]
	v_or_b32_e32 v211, 3, v191
	v_mfma_f32_16x16x32_bf16 v[170:173], v[36:39], v[100:103], v[116:119]
	v_mfma_f32_16x16x32_bf16 v[128:131], v[198:201], v[206:209], v[218:221]
	v_mfma_f32_16x16x32_bf16 v[124:127], v[198:201], v[88:91], v[222:225]
	v_mfma_f32_16x16x32_bf16 v[120:123], v[198:201], v[100:103], v[226:229]
	v_mfma_f32_16x16x32_bf16 v[116:119], v[198:201], v[52:55], v[230:233]
	v_or_b32_e32 v198, 48, v160
	v_or_b32_e32 v160, v190, v180
	v_lshlrev_b32_e32 v160, 2, v160
	global_load_dword v193, v160, s[10:11]
	v_lshl_add_u64 v[178:179], s[10:11], 0, v[160:161]
	v_mfma_f32_16x16x32_bf16 v[166:169], v[36:39], v[52:55], v[0:3]
	v_lshl_or_b32 v185, v198, 2, v189
	s_waitcnt vmcnt(0)
	v_add_f32_e32 v186, v204, v193
	v_max_f32_e32 v186, 0, v186
	v_mul_f32_e32 v188, v186, v186
	v_add_f32_e32 v186, v205, v193
	v_add_f32_e32 v160, v202, v193
	v_max_f32_e32 v186, 0, v186
	v_max_f32_e32 v160, 0, v160
	v_add_f32_e32 v181, v203, v193
	v_mul_f32_e32 v194, v186, v186
	v_lshl_or_b32 v186, v180, 2, v189
	v_mul_f32_e32 v160, v160, v160
	v_max_f32_e32 v181, 0, v181
	v_mad_u32_u24 v192, v195, s35, v186
	v_mul_f32_e32 v181, v181, v181
	ds_write_b32 v192, v160
	ds_write_b32 v192, v181 offset:272
	ds_write_b32 v192, v188 offset:544
	v_mad_u32_u24 v199, v211, s35, v186
	v_add_lshl_u32 v160, v190, v180, 2
	ds_write_b32 v199, v194
	global_load_dword v194, v160, s[10:11] offset:64
	v_lshl_add_u64 v[180:181], s[10:11], 0, v[160:161]
	v_mfma_f32_16x16x32_bf16 v[148:151], v[48:51], v[52:55], v[92:95]
	v_add_f32_e32 v162, v162, v193
	v_add_f32_e32 v163, v163, v193
	v_max_f32_e32 v162, 0, v162
	v_max_f32_e32 v163, 0, v163
	v_add_f32_e32 v164, v164, v193
	v_mul_f32_e32 v162, v162, v162
	v_mul_f32_e32 v163, v163, v163
	v_max_f32_e32 v164, 0, v164
	v_add_f32_e32 v165, v165, v193
	v_mul_f32_e32 v164, v164, v164
	v_max_f32_e32 v165, 0, v165
	v_mul_f32_e32 v165, v165, v165
	v_add_f32_e32 v144, v144, v193
	v_add_f32_e32 v145, v145, v193
	v_max_f32_e32 v144, 0, v144
	v_max_f32_e32 v145, 0, v145
	v_add_f32_e32 v146, v146, v193
	v_mul_f32_e32 v144, v144, v144
	v_mul_f32_e32 v145, v145, v145
	v_max_f32_e32 v146, 0, v146
	v_add_f32_e32 v147, v147, v193
	v_mul_f32_e32 v146, v146, v146
	v_max_f32_e32 v147, 0, v147
	v_mul_f32_e32 v147, v147, v147
	v_add_f32_e32 v128, v128, v193
	v_add_f32_e32 v129, v129, v193
	v_max_f32_e32 v128, 0, v128
	v_max_f32_e32 v129, 0, v129
	v_add_f32_e32 v130, v130, v193
	v_mul_f32_e32 v128, v128, v128
	v_mul_f32_e32 v129, v129, v129
	v_max_f32_e32 v130, 0, v130
	v_add_f32_e32 v131, v131, v193
	v_mul_f32_e32 v130, v130, v130
	v_max_f32_e32 v131, 0, v131
	v_mul_f32_e32 v131, v131, v131
	v_mfma_f32_16x16x32_bf16 v[92:95], v[112:115], v[206:209], v[234:237]
	v_mul_u32_u24_e32 v188, 0x110, v211
	s_waitcnt vmcnt(0)
	v_add_f32_e32 v174, v174, v194
	v_max_f32_e32 v174, 0, v174
	v_add_f32_e32 v175, v175, v194
	v_add_f32_e32 v176, v176, v194
	v_add_f32_e32 v177, v177, v194
	v_mul_f32_e32 v174, v174, v174
	v_max_f32_e32 v175, 0, v175
	v_max_f32_e32 v176, 0, v176
	v_max_f32_e32 v177, 0, v177
	v_mul_f32_e32 v175, v175, v175
	v_mul_f32_e32 v176, v176, v176
	v_mul_f32_e32 v177, v177, v177
	ds_write_b32 v192, v174 offset:64
	ds_write_b32 v192, v175 offset:336
	ds_write_b32 v192, v176 offset:608
	ds_write_b32 v199, v177 offset:64
	global_load_dword v174, v160, s[10:11] offset:128
	v_add_f32_e32 v156, v156, v194
	v_max_f32_e32 v156, 0, v156
	v_add_f32_e32 v157, v157, v194
	v_add_f32_e32 v158, v158, v194
	v_add_f32_e32 v159, v159, v194
	v_mul_f32_e32 v156, v156, v156
	v_max_f32_e32 v157, 0, v157
	v_max_f32_e32 v158, 0, v158
	v_max_f32_e32 v159, 0, v159
	v_mul_f32_e32 v157, v157, v157
	v_mul_f32_e32 v158, v158, v158
	v_mul_f32_e32 v159, v159, v159
	v_add_f32_e32 v140, v140, v194
	v_max_f32_e32 v140, 0, v140
	v_add_f32_e32 v141, v141, v194
	v_add_f32_e32 v142, v142, v194
	v_add_f32_e32 v143, v143, v194
	v_mul_f32_e32 v140, v140, v140
	v_max_f32_e32 v141, 0, v141
	v_max_f32_e32 v142, 0, v142
	v_max_f32_e32 v143, 0, v143
	v_mul_f32_e32 v141, v141, v141
	v_mul_f32_e32 v142, v142, v142
	v_mul_f32_e32 v143, v143, v143
	v_add_f32_e32 v124, v124, v194
	v_max_f32_e32 v124, 0, v124
	v_add_f32_e32 v125, v125, v194
	v_add_f32_e32 v126, v126, v194
	v_add_f32_e32 v127, v127, v194
	v_mul_f32_e32 v124, v124, v124
	v_max_f32_e32 v125, 0, v125
	v_max_f32_e32 v126, 0, v126
	v_max_f32_e32 v127, 0, v127
	v_mul_f32_e32 v125, v125, v125
	v_mul_f32_e32 v126, v126, v126
	v_mul_f32_e32 v127, v127, v127
	v_mfma_f32_16x16x32_bf16 v[48:51], v[108:111], v[206:209], v[238:241]
	s_waitcnt vmcnt(0)
; template <int EPI>
; DI void epilogue_tile(const EpiArgs& e, int row0, int wrow, int wcol, f32x4 (&acc)[4][4], char* smem, const float* rsm, int wave, int lane,
;                       bool final_sync = true) {
;     ...
;       if constexpr (EPI == EPI_FF1) {
;         const float bb = e.bias[col];
; #pragma unroll
;         for (int j = 0; j < 4; ++j) { const float t = fmaxf(v[j] + bb, 0.f); v[j] = t * t; }
;       }
;       if (transposed) {
;         *(f32x4*)(stage + lcol * STG + lrow) = (f32x4){v[0], v[1], v[2], v[3]};
;       } else {
; #pragma unroll
;         for (int j = 0; j < 4; ++j) stage[(lrow + j) * STG + lcol] = v[j];
;       }
;     }
;   const int rr = lane >> 3, c8 = (lane & 7) * 8;
; #pragma unroll 4
;   for (int it = 0; it < 8; ++it) {
;     const int sr = it * 8 + rr;
;     const f32x4 v0 = *(const f32x4*)(stage + sr * STG + c8);
	v_add_f32_e32 v160, v170, v174
	v_max_f32_e32 v160, 0, v160
	v_add_f32_e32 v170, v171, v174
	v_add_f32_e32 v171, v172, v174
	v_add_f32_e32 v172, v173, v174
	v_mul_f32_e32 v160, v160, v160
	v_max_f32_e32 v170, 0, v170
	v_max_f32_e32 v171, 0, v171
	v_max_f32_e32 v172, 0, v172
	v_mul_f32_e32 v170, v170, v170
	v_mul_f32_e32 v171, v171, v171
	v_mul_f32_e32 v172, v172, v172
	ds_write_b32 v192, v160 offset:128
	ds_write_b32 v192, v170 offset:400
	ds_write_b32 v192, v171 offset:672
	ds_write_b32 v199, v172 offset:128
	v_or_b32_e32 v160, v190, v198
	v_lshlrev_b32_e32 v160, 2, v160
	v_lshl_add_u64 v[170:171], s[10:11], 0, v[160:161]
	global_load_dword v160, v160, s[10:11]
	v_mad_u32_u24 v172, v195, s35, v185
	v_add_f32_e32 v152, v152, v174
	v_max_f32_e32 v152, 0, v152
	v_add_f32_e32 v153, v153, v174
	v_add_f32_e32 v154, v154, v174
	v_add_f32_e32 v155, v155, v174
	v_mul_f32_e32 v152, v152, v152
	v_max_f32_e32 v153, 0, v153
	v_max_f32_e32 v154, 0, v154
	v_max_f32_e32 v155, 0, v155
	v_mul_f32_e32 v153, v153, v153
	v_mul_f32_e32 v154, v154, v154
	v_mul_f32_e32 v155, v155, v155
	v_add_f32_e32 v136, v136, v174
	v_max_f32_e32 v136, 0, v136
	v_add_f32_e32 v137, v137, v174
	v_add_f32_e32 v138, v138, v174
	v_add_f32_e32 v139, v139, v174
	v_mul_f32_e32 v136, v136, v136
	v_max_f32_e32 v137, 0, v137
	v_max_f32_e32 v138, 0, v138
	v_max_f32_e32 v139, 0, v139
	v_mul_f32_e32 v137, v137, v137
	v_mul_f32_e32 v138, v138, v138
	v_mul_f32_e32 v139, v139, v139
	v_add_f32_e32 v120, v120, v174
	v_max_f32_e32 v120, 0, v120
	v_add_f32_e32 v121, v121, v174
	v_add_f32_e32 v122, v122, v174
	v_add_f32_e32 v123, v123, v174
	v_mul_f32_e32 v120, v120, v120
	v_max_f32_e32 v121, 0, v121
	v_max_f32_e32 v122, 0, v122
	v_max_f32_e32 v123, 0, v123
	v_mul_f32_e32 v121, v121, v121
	v_mul_f32_e32 v122, v122, v122
	v_mul_f32_e32 v123, v123, v123
	v_mfma_f32_16x16x32_bf16 v[36:39], v[104:107], v[206:209], v[242:245]
	s_waitcnt vmcnt(0)
	v_add_f32_e32 v166, v166, v160
	v_add_f32_e32 v167, v167, v160
	v_max_f32_e32 v166, 0, v166
	v_max_f32_e32 v167, 0, v167
	v_add_f32_e32 v168, v168, v160
	v_add_f32_e32 v169, v169, v160
	v_mul_f32_e32 v166, v166, v166
	v_mul_f32_e32 v167, v167, v167
	v_max_f32_e32 v168, 0, v168
	v_max_f32_e32 v169, 0, v169
	v_mul_f32_e32 v168, v168, v168
	v_mul_f32_e32 v169, v169, v169
	ds_write2_b32 v172, v166, v167 offset1:68
	ds_write_b32 v172, v168 offset:544
	v_mad_u32_u24 v166, v211, s35, v185
	ds_write_b32 v166, v169
	ds_write_b32 v192, v162 offset:4352
	ds_write_b32 v192, v163 offset:4624
	ds_write_b32 v192, v164 offset:4896
	v_or_b32_e32 v163, 19, v191
	v_add_f32_e32 v148, v148, v160
	v_add_f32_e32 v149, v149, v160
	v_mad_u32_u24 v164, v163, s35, v186
	v_max_f32_e32 v148, 0, v148
	v_max_f32_e32 v149, 0, v149
	v_add_f32_e32 v150, v150, v160
	v_add_f32_e32 v151, v151, v160
	ds_write_b32 v164, v165
	ds_write_b32 v192, v156 offset:4416
	ds_write_b32 v192, v157 offset:4688
	ds_write_b32 v192, v158 offset:4960
	ds_write_b32 v164, v159 offset:64
	ds_write_b32 v192, v152 offset:4480
	ds_write_b32 v192, v153 offset:4752
	ds_write_b32 v192, v154 offset:5024
	ds_write_b32 v164, v155 offset:128
	v_mul_f32_e32 v148, v148, v148
	v_mul_f32_e32 v149, v149, v149
	v_max_f32_e32 v150, 0, v150
	v_max_f32_e32 v151, 0, v151
	v_add_u32_e32 v152, 0x1000, v172
	v_mul_f32_e32 v150, v150, v150
	v_mul_f32_e32 v151, v151, v151
	ds_write2_b32 v152, v148, v149 offset0:64 offset1:132
	ds_write_b32 v172, v150 offset:4896
	v_mad_u32_u24 v148, v163, s35, v185
	ds_write_b32 v148, v151
	ds_write_b32 v192, v144 offset:8704
	ds_write_b32 v192, v145 offset:8976
	ds_write_b32 v192, v146 offset:9248
	v_or_b32_e32 v145, 35, v191
	v_add_f32_e32 v132, v132, v160
	v_add_f32_e32 v133, v133, v160
	v_mad_u32_u24 v146, v145, s35, v186
	v_max_f32_e32 v132, 0, v132
	v_max_f32_e32 v133, 0, v133
	v_add_f32_e32 v134, v134, v160
	v_add_f32_e32 v135, v135, v160
	ds_write_b32 v146, v147
	ds_write_b32 v192, v140 offset:8768
	ds_write_b32 v192, v141 offset:9040
	ds_write_b32 v192, v142 offset:9312
	ds_write_b32 v146, v143 offset:64
	ds_write_b32 v192, v136 offset:8832
	ds_write_b32 v192, v137 offset:9104
	ds_write_b32 v192, v138 offset:9376
	ds_write_b32 v146, v139 offset:128
	v_mul_f32_e32 v132, v132, v132
	v_mul_f32_e32 v133, v133, v133
	v_max_f32_e32 v134, 0, v134
	v_max_f32_e32 v135, 0, v135
	v_add_u32_e32 v136, 0x2000, v172
	v_mul_f32_e32 v134, v134, v134
	v_mul_f32_e32 v135, v135, v135
	ds_write2_b32 v136, v132, v133 offset0:128 offset1:196
	ds_write_b32 v172, v134 offset:9248
	v_mad_u32_u24 v132, v145, s35, v185
	ds_write_b32 v132, v135
	ds_write_b32 v192, v128 offset:13056
	ds_write_b32 v192, v129 offset:13328
	ds_write_b32 v192, v130 offset:13600
	v_or_b32_e32 v129, 51, v191
	v_add_f32_e32 v116, v116, v160
	v_add_f32_e32 v117, v117, v160
	v_mad_u32_u24 v130, v129, s35, v186
	v_max_f32_e32 v116, 0, v116
	v_max_f32_e32 v117, 0, v117
	v_add_f32_e32 v118, v118, v160
	v_add_f32_e32 v119, v119, v160
	ds_write_b32 v130, v131
	ds_write_b32 v192, v124 offset:13120
	ds_write_b32 v192, v125 offset:13392
	ds_write_b32 v192, v126 offset:13664
	ds_write_b32 v130, v127 offset:64
	ds_write_b32 v192, v120 offset:13184
	ds_write_b32 v192, v121 offset:13456
	ds_write_b32 v192, v122 offset:13728
	ds_write_b32 v130, v123 offset:128
	v_mul_f32_e32 v116, v116, v116
	v_mul_f32_e32 v117, v117, v117
	v_max_f32_e32 v118, 0, v118
	v_max_f32_e32 v119, 0, v119
	v_add_u32_e32 v120, 0x3200, v172
	v_mul_f32_e32 v118, v118, v118
	v_mul_f32_e32 v119, v119, v119
	ds_write2_b32 v120, v116, v117 offset0:64 offset1:132
	ds_write_b32 v172, v118 offset:13600
	v_mad_u32_u24 v116, v129, s35, v185
	v_mfma_f32_16x16x32_bf16 v[0:3], v[96:99], v[206:209], v[246:249]
	ds_write_b32 v116, v119
	v_bfe_u32 v119, v182, 3, 3
	v_and_b32_e32 v120, 7, v182
	v_lshlrev_b32_e32 v160, 1, v190
	v_add3_u32 v118, v119, s15, v183
	v_mul_u32_u24_e32 v119, 0x110, v119
	v_lshlrev_b32_e32 v120, 5, v120
	v_lshl_add_u64 v[116:117], s[56:57], 0, v[160:161]
	v_and_b32_e32 v160, 0x70, v184
	v_add3_u32 v119, v189, v119, v120
	v_mul_u32_u24_e32 v162, 0x110, v163
	v_mul_u32_u24_e32 v144, 0x110, v145
	v_mul_u32_u24_e32 v128, 0x110, v129
	v_lshl_add_u64 v[116:117], v[116:117], 0, v[160:161]
	v_mov_b32_e32 v120, v119

; DI int otid() { int t = threadIdx.x; asm volatile("" : "+v"(t)); return t; }
; #define GEMM_DMA(kt) { GEMM_DMA_A(kt) GEMM_DMA_B(kt) }
; template <int EPI>
; __device__ __forceinline__ void gemm_tile_dma(const bft* __restrict__ A, int lda, const bft* __restrict__ Bt, int K, int row0, int col0,
;                                               char* smem, const EpiArgs& e) {
;   const int tid = otid(), wave = tid >> 6, lane = tid & 63;
;   const int wm = wave >> 2, wn = wave & 3, r16 = lane & 15, g = lane >> 4;
;   f32x4 accL[4][4], accH[4][4];
; #pragma unroll
;   for (int i = 0; i < 4; ++i)
; #pragma unroll
;     for (int j = 0; j < 4; ++j) { accL[i][j] = (f32x4){0.f, 0.f, 0.f, 0.f}; accH[i][j] = (f32x4){0.f, 0.f, 0.f, 0.f}; }
;   const int lr = tid >> 2, pc = tid & 3;
;   const int kcs = (pc ^ ((4 - ((lr >> 2) & 3)) & 3)) * 8;
;   const int rco = (g ^ ((4 - ((r16 >> 2) & 3)) & 3)) * 8;
;   const bft* ag = A + (size_t)(row0 + lr) * lda + kcs;
;   const bft* bg = Bt + (size_t)(col0 + lr) * K + kcs;
;   const unsigned lds_a = (unsigned)(size_t)smem + (unsigned)(((wm * 128 + r16) * 32 + rco) * 2);
;   const unsigned lds_b = (unsigned)(size_t)smem + 16384u + (unsigned)(((wn * 64 + r16) * 32 + rco) * 2);
;   const int nk = K / 32;
;     ...
;   GEMM_DMA(0);
;   GEMM_DMA(1);
;   GEMM_DMA(2);
;   for (int kt = 0; kt < nk; ++kt) {
;     if (kt + 2 < nk) asm volatile("s_waitcnt vmcnt(8)" ::: "memory");
;     else if (kt + 1 < nk) asm volatile("s_waitcnt vmcnt(4)" ::: "memory");
;     else asm volatile("s_waitcnt vmcnt(0)" ::: "memory");
;     __builtin_amdgcn_s_barrier();
.LBB0_1327:
	s_lshr_b32 s13, s14, 2
	s_and_b32 s12, s14, 31
	s_and_b32 s13, s13, 56
	s_cmpk_lt_u32 s14, 0x80
	s_cselect_b32 s15, 7, 1
	s_cselect_b32 s17, 3, 1
	s_and_b32 s15, s15, s14
	s_add_i32 s16, s3, s15
	s_add_i32 s16, s16, s13
	v_mov_b32_e32 v188, v196
	s_lshl_b32 s15, s16, 8
	s_lshr_b32 s12, s12, s17
	v_ashrrev_i32_e32 v4, 2, v188
	v_lshrrev_b32_e32 v0, 4, v188
	v_sub_u32_e32 v10, 0, v0
	v_add_u32_e32 v0, s15, v4
	v_xor_b32_e32 v5, v188, v10
	v_ashrrev_i32_e32 v1, 31, v0
	v_lshlrev_b64 v[0:1], 13, v[0:1]
	v_lshlrev_b32_e32 v5, 4, v5
	v_lshlrev_b32_e32 v190, 4, v188
	s_lshl_b32 s17, s12, 8
	v_lshl_add_u64 v[2:3], s[56:57], 0, v[0:1]
	v_and_b32_e32 v160, 48, v5
	v_readfirstlane_b32 s12, v190
	v_add_u32_e32 v11, 0x2000, v190
	v_lshl_add_u64 v[2:3], v[2:3], 0, v[160:161]
	v_add_u32_e32 v4, s17, v4
	v_ashrrev_i32_e32 v8, 1, v188
	s_mov_b32 m0, s12
	s_mov_b64 s[38:39], 0x100000
	v_readfirstlane_b32 s12, v11
	v_ashrrev_i32_e32 v5, 31, v4
	v_and_b32_e32 v189, 0xffffff80, v8
	global_load_lds_dwordx4 v[2:3], off
	v_lshl_add_u64 v[8:9], v[2:3], 0, s[38:39]
	s_mov_b32 m0, s12
	v_lshlrev_b64 v[4:5], 13, v[4:5]
	global_load_lds_dwordx4 v[8:9], off
	v_add_u32_e32 v8, 0x4000, v190
	v_lshl_add_u64 v[6:7], s[24:25], 0, v[4:5]
	v_readfirstlane_b32 s12, v8
	v_add_u32_e32 v11, 0x6000, v190
	v_lshl_add_u64 v[6:7], v[6:7], 0, v[160:161]
	s_mov_b32 m0, s12
	v_readfirstlane_b32 s12, v11
	v_add_u32_e32 v11, 0x8000, v190
	global_load_lds_dwordx4 v[6:7], off
	v_lshl_add_u64 v[8:9], v[6:7], 0, s[38:39]
	s_mov_b32 m0, s12
	v_readfirstlane_b32 s12, v11
	v_add_u32_e32 v11, 0xa000, v190
	global_load_lds_dwordx4 v[8:9], off
	v_lshl_add_u64 v[8:9], v[2:3], 0, 64
	s_mov_b32 m0, s12
	s_mov_b64 s[38:39], 0x100040
	v_readfirstlane_b32 s12, v11
	v_add_u32_e32 v11, 0xc000, v190
	global_load_lds_dwordx4 v[8:9], off
	v_lshl_add_u64 v[8:9], v[2:3], 0, s[38:39]
	s_mov_b32 m0, s12
	v_readfirstlane_b32 s12, v11
	v_add_u32_e32 v11, 0xe000, v190
	global_load_lds_dwordx4 v[8:9], off
	v_lshl_add_u64 v[8:9], v[6:7], 0, 64
	s_mov_b32 m0, s12
	v_readfirstlane_b32 s12, v11
	v_add_u32_e32 v11, 0x10000, v190
	global_load_lds_dwordx4 v[8:9], off
	v_lshl_add_u64 v[8:9], v[6:7], 0, s[38:39]
	s_mov_b32 m0, s12
	s_mov_b64 s[38:39], 0x80
	v_readfirstlane_b32 s12, v11
	global_load_lds_dwordx4 v[8:9], off
	v_lshl_add_u64 v[8:9], v[2:3], 0, s[38:39]
	s_mov_b32 m0, s12
	s_mov_b64 s[40:41], 0x100080
	global_load_lds_dwordx4 v[8:9], off
	v_add_u32_e32 v8, 0x12000, v190
	v_lshl_add_u64 v[2:3], v[2:3], 0, s[40:41]
	v_readfirstlane_b32 s12, v8
	v_add_u32_e32 v8, 0x14000, v190
	s_mov_b32 m0, s12
	v_readfirstlane_b32 s12, v8
	global_load_lds_dwordx4 v[2:3], off
	v_lshl_add_u64 v[2:3], v[6:7], 0, s[38:39]
	s_mov_b32 m0, s12
	v_and_b32_e32 v182, 15, v188
	global_load_lds_dwordx4 v[2:3], off
	v_lshl_add_u64 v[2:3], v[6:7], 0, s[40:41]
	v_add_u32_e32 v6, 0x16000, v190
	v_mov_b32_e32 v28, 0
	v_readfirstlane_b32 s12, v6
	s_mov_b32 m0, s12
	v_lshlrev_b32_e32 v6, 6, v188
	global_load_lds_dwordx4 v[2:3], off
	v_lshlrev_b32_e32 v2, 2, v188
	v_and_b32_e32 v2, 48, v2
	v_sub_u32_e32 v2, 0, v2
	v_bitop3_b32 v2, v188, 48, v2 bitop3:0x48
	v_or_b32_e32 v3, v189, v182
	v_and_b32_e32 v6, 0x33c0, v6
	v_lshl_or_b32 v133, v3, 6, v2
	v_or3_b32 v132, v6, v2, s42
	v_bitop3_b32 v2, v188, 3, v10 bitop3:0x48
	v_lshlrev_b32_e32 v2, 4, v2
	v_or_b32_e32 v4, v4, v2
	v_or_b32_e32 v0, v0, v2
	v_mov_b32_e32 v237, 0x2200
	v_not_b32_e32 v236, 63
	v_mov_b32_e32 v235, 0x42800000
	v_mov_b32_e32 v234, 0x22000
	s_mov_b32 s27, 0
	s_waitcnt vmcnt(0)
	v_lshl_add_u64 v[128:129], s[90:91], 0, v[4:5]
	v_lshl_add_u64 v[130:131], s[90:91], 0, v[0:1]
	s_mov_b64 s[12:13], 0
	v_mov_b32_e32 v29, v28
	v_mov_b32_e32 v30, v28
	v_mov_b32_e32 v31, v28
	v_mov_b32_e32 v32, v28
	v_mov_b32_e32 v33, v28
	v_mov_b32_e32 v34, v28
	v_mov_b32_e32 v35, v28
	v_mov_b32_e32 v24, v28
	v_mov_b32_e32 v25, v28
	v_mov_b32_e32 v26, v28
	v_mov_b32_e32 v27, v28
	v_mov_b32_e32 v36, v28
	v_mov_b32_e32 v37, v28
	v_mov_b32_e32 v38, v28
	v_mov_b32_e32 v39, v28
	v_mov_b32_e32 v20, v28
	v_mov_b32_e32 v21, v28
	v_mov_b32_e32 v22, v28
	v_mov_b32_e32 v23, v28
	v_mov_b32_e32 v40, v28
	v_mov_b32_e32 v41, v28
	v_mov_b32_e32 v42, v28
	v_mov_b32_e32 v43, v28
	v_mov_b32_e32 v16, v28
	v_mov_b32_e32 v17, v28
	v_mov_b32_e32 v18, v28
	v_mov_b32_e32 v19, v28
	v_mov_b32_e32 v44, v28
	v_mov_b32_e32 v45, v28
	v_mov_b32_e32 v46, v28
	v_mov_b32_e32 v47, v28
	v_mov_b32_e32 v12, v28
	v_mov_b32_e32 v13, v28
	v_mov_b32_e32 v14, v28
	v_mov_b32_e32 v15, v28
	v_mov_b32_e32 v48, v28
	v_mov_b32_e32 v49, v28
	v_mov_b32_e32 v50, v28
	v_mov_b32_e32 v51, v28
	v_mov_b32_e32 v8, v28
	v_mov_b32_e32 v9, v28
	v_mov_b32_e32 v10, v28
	v_mov_b32_e32 v11, v28
	v_mov_b32_e32 v52, v28
	v_mov_b32_e32 v53, v28
	v_mov_b32_e32 v54, v28
	v_mov_b32_e32 v55, v28
	v_mov_b32_e32 v4, v28
	v_mov_b32_e32 v5, v28
	v_mov_b32_e32 v6, v28
	v_mov_b32_e32 v7, v28
	v_mov_b32_e32 v56, v28
	v_mov_b32_e32 v57, v28
	v_mov_b32_e32 v58, v28
	v_mov_b32_e32 v59, v28
	v_mov_b32_e32 v0, v28
	v_mov_b32_e32 v1, v28
	v_mov_b32_e32 v2, v28
	v_mov_b32_e32 v3, v28
	v_mov_b32_e32 v60, v28
	v_mov_b32_e32 v61, v28
	v_mov_b32_e32 v62, v28
	v_mov_b32_e32 v63, v28
	v_mov_b32_e32 v64, v28
	v_mov_b32_e32 v65, v28
	v_mov_b32_e32 v66, v28
	v_mov_b32_e32 v67, v28
	v_mov_b32_e32 v68, v28
	v_mov_b32_e32 v69, v28
	v_mov_b32_e32 v70, v28
	v_mov_b32_e32 v71, v28
	v_mov_b32_e32 v72, v28
	v_mov_b32_e32 v73, v28
	v_mov_b32_e32 v74, v28
	v_mov_b32_e32 v75, v28
	v_mov_b32_e32 v76, v28
	v_mov_b32_e32 v77, v28
	v_mov_b32_e32 v78, v28
	v_mov_b32_e32 v79, v28
	v_mov_b32_e32 v80, v28
	v_mov_b32_e32 v81, v28
	v_mov_b32_e32 v82, v28
	v_mov_b32_e32 v83, v28
	v_mov_b32_e32 v84, v28
	v_mov_b32_e32 v85, v28
	v_mov_b32_e32 v86, v28
	v_mov_b32_e32 v87, v28
	v_mov_b32_e32 v88, v28
	v_mov_b32_e32 v89, v28
	v_mov_b32_e32 v90, v28
	v_mov_b32_e32 v91, v28
	v_mov_b32_e32 v92, v28
	v_mov_b32_e32 v93, v28
	v_mov_b32_e32 v94, v28
	v_mov_b32_e32 v95, v28
	v_mov_b32_e32 v96, v28
	v_mov_b32_e32 v97, v28
	v_mov_b32_e32 v98, v28
	v_mov_b32_e32 v99, v28
	v_mov_b32_e32 v100, v28
	v_mov_b32_e32 v101, v28
	v_mov_b32_e32 v102, v28
	v_mov_b32_e32 v103, v28
	v_mov_b32_e32 v104, v28
	v_mov_b32_e32 v105, v28
	v_mov_b32_e32 v106, v28
	v_mov_b32_e32 v107, v28
	v_mov_b32_e32 v108, v28
	v_mov_b32_e32 v109, v28
	v_mov_b32_e32 v110, v28
	v_mov_b32_e32 v111, v28
	v_mov_b32_e32 v116, v28
	v_mov_b32_e32 v117, v28
	v_mov_b32_e32 v118, v28
	v_mov_b32_e32 v119, v28
	v_mov_b32_e32 v120, v28
	v_mov_b32_e32 v121, v28
	v_mov_b32_e32 v122, v28
	v_mov_b32_e32 v123, v28
	v_mov_b32_e32 v124, v28
	v_mov_b32_e32 v125, v28
	v_mov_b32_e32 v126, v28
	v_mov_b32_e32 v127, v28
	v_mov_b32_e32 v112, v28
	v_mov_b32_e32 v113, v28
	v_mov_b32_e32 v114, v28
	v_mov_b32_e32 v115, v28
	s_and_b32 s34, s27, 0x18000
	v_add_u32_e32 v158, s34, v133
	v_or_b32_e32 v159, s34, v132
	s_waitcnt vmcnt(8)
	s_barrier
; #define ROW4(accv, r, av)                                                                              \
;     accv[r][0] = MFMA16(av, b0, accv[r][0]); accv[r][1] = MFMA16(av, b1, accv[r][1]);                      \
;     accv[r][2] = MFMA16(av, b2, accv[r][2]); accv[r][3] = MFMA16(av, b3, accv[r][3]);
; template <int EPI>
; __device__ __forceinline__ void gemm_tile_dma(const bft* __restrict__ A, int lda, const bft* __restrict__ Bt, int K, int row0, int col0,
;                                               char* smem, const EpiArgs& e) {
;     ...
;   for (int kt = 0; kt < nk; ++kt) {
;     if (kt + 2 < nk) asm volatile("s_waitcnt vmcnt(8)" ::: "memory");
;     else if (kt + 1 < nk) asm volatile("s_waitcnt vmcnt(4)" ::: "memory");
;     else asm volatile("s_waitcnt vmcnt(0)" ::: "memory");
;     __builtin_amdgcn_s_barrier();
;     asm volatile("" ::: "memory");
;     const bool pf = kt + 3 < nk;
;     const unsigned so = (unsigned)(kt & 3) * GST;
;     bf16x8 a0, a1, a2, a3, b0, b1, b2, b3;
;     asm volatile(
;         "ds_read_b128 %0, %8\n\t"
;         "ds_read_b128 %1, %8 offset:1024\n\t"
;         "ds_read_b128 %2, %8 offset:2048\n\t"
;         "ds_read_b128 %3, %8 offset:3072\n\t"
;         "ds_read_b128 %4, %9\n\t"
;         "ds_read_b128 %5, %9 offset:1024\n\t"
;         "ds_read_b128 %6, %9 offset:2048\n\t"
;         "ds_read_b128 %7, %9 offset:3072\n\t"
;         "s_waitcnt lgkmcnt(0)"
;         : "=&v"(a0), "=&v"(a1), "=&v"(a2), "=&v"(a3), "=&v"(b0), "=&v"(b1), "=&v"(b2), "=&v"(b3)
;         : "v"(lds_a + so), "v"(lds_b + so)
;         : "memory");
;     ...
;     ROW4(accL, 0, a0) ROW4(accL, 1, a1)
;     if (pf) GEMM_DMA_A(kt + 3)
;     ROW4(accL, 2, a2) ROW4(accL, 3, a3)
;     asm volatile(
;         "ds_read_b128 %0, %4 offset:4096\n\t"
;         "ds_read_b128 %1, %4 offset:5120\n\t"
;         "ds_read_b128 %2, %4 offset:6144\n\t"
;         "ds_read_b128 %3, %4 offset:7168\n\t"
;         "s_waitcnt lgkmcnt(0)"
;         : "=&v"(a0), "=&v"(a1), "=&v"(a2), "=&v"(a3)
;         : "v"(lds_a + so)
;         : "memory");
;     ROW4(accH, 0, a0) ROW4(accH, 1, a1)
;     if (pf) GEMM_DMA_B(kt + 3)
;     ROW4(accH, 2, a2) ROW4(accH, 3, a3)
;     ...
;   }
	ds_read_b128 v[134:137], v158
	ds_read_b128 v[138:141], v158 offset:1024
	ds_read_b128 v[142:145], v158 offset:2048
	ds_read_b128 v[146:149], v158 offset:3072
	ds_read_b128 v[150:153], v159
	ds_read_b128 v[154:157], v159 offset:1024
	ds_read_b128 v[162:165], v159 offset:2048
	ds_read_b128 v[166:169], v159 offset:3072
.LBB0_1328:
	s_and_b32 s34, s27, 0x18000
	v_add_u32_e32 v158, s34, v133
	ds_read_b128 v[172:175], v158 offset:4096
	ds_read_b128 v[176:179], v158 offset:5120
	ds_read_b128 v[184:187], v158 offset:6144
	ds_read_b128 v[192:195], v158 offset:7168
	v_or_b32_e32 v159, s34, v132
	s_add_i32 s34, s27, 0x18000
	s_waitcnt lgkmcnt(4)
	s_and_b32 s34, s34, 0x18000
	v_mfma_f32_16x16x32_bf16 v[124:127], v[134:137], v[150:153], v[124:127]
	s_mov_b64 s[38:39], 0x198000c0
	v_add_u32_e32 v159, s34, v190
	v_mfma_f32_16x16x32_bf16 v[120:123], v[134:137], v[154:157], v[120:123]
	v_readfirstlane_b32 s34, v159
	s_mov_b32 m0, s34
	v_mfma_f32_16x16x32_bf16 v[116:119], v[134:137], v[162:165], v[116:119]
	v_mfma_f32_16x16x32_bf16 v[108:111], v[134:137], v[166:169], v[108:111]
	v_lshl_add_u64 v[134:135], v[130:131], 0, s[12:13]
	v_lshl_add_u64 v[136:137], v[134:135], 0, s[38:39]
	s_mov_b64 s[38:39], 0x199000c0
	v_mfma_f32_16x16x32_bf16 v[104:107], v[138:141], v[150:153], v[104:107]
	v_lshl_add_u64 v[134:135], v[134:135], 0, s[38:39]
	global_load_lds_dwordx4 v[136:137], off
	v_mfma_f32_16x16x32_bf16 v[100:103], v[138:141], v[154:157], v[100:103]
	v_mfma_f32_16x16x32_bf16 v[96:99], v[138:141], v[162:165], v[96:99]
	v_mfma_f32_16x16x32_bf16 v[92:95], v[138:141], v[166:169], v[92:95]
	v_add_u32_e32 v138, 0x2000, v159
	s_nop 0
	v_readfirstlane_b32 s38, v138
	s_mov_b32 m0, s38
	v_mfma_f32_16x16x32_bf16 v[88:91], v[142:145], v[150:153], v[88:91]
	global_load_lds_dwordx4 v[134:135], off
	s_mov_b64 s[38:39], 0x3c7800c0
	v_mfma_f32_16x16x32_bf16 v[84:87], v[142:145], v[154:157], v[84:87]
	v_mfma_f32_16x16x32_bf16 v[80:83], v[142:145], v[162:165], v[80:83]
	v_mfma_f32_16x16x32_bf16 v[76:79], v[142:145], v[166:169], v[76:79]
	v_mfma_f32_16x16x32_bf16 v[72:75], v[146:149], v[150:153], v[72:75]
	v_mfma_f32_16x16x32_bf16 v[68:71], v[146:149], v[154:157], v[68:71]
	v_mfma_f32_16x16x32_bf16 v[64:67], v[146:149], v[162:165], v[64:67]
	v_mfma_f32_16x16x32_bf16 v[60:63], v[146:149], v[166:169], v[60:63]
	s_waitcnt lgkmcnt(0)
	s_waitcnt vmcnt(6)
	s_barrier
	s_add_i32 s32, s27, 0x8000
	s_and_b32 s32, s32, 0x18000
	v_add_u32_e32 v160, s32, v133
	v_or_b32_e32 v170, s32, v132
	ds_read_b128 v[200:203], v160
	ds_read_b128 v[204:207], v160 offset:1024
	ds_read_b128 v[208:211], v160 offset:2048
	ds_read_b128 v[212:215], v160 offset:3072
	ds_read_b128 v[216:219], v170
	ds_read_b128 v[220:223], v170 offset:1024
	ds_read_b128 v[224:227], v170 offset:2048
	ds_read_b128 v[228:231], v170 offset:3072
	s_nop 0
	v_mfma_f32_16x16x32_bf16 v[112:115], v[172:175], v[150:153], v[112:115]
	v_mfma_f32_16x16x32_bf16 v[0:3], v[172:175], v[154:157], v[0:3]
	v_mfma_f32_16x16x32_bf16 v[56:59], v[172:175], v[162:165], v[56:59]
	v_mfma_f32_16x16x32_bf16 v[4:7], v[172:175], v[166:169], v[4:7]
	v_lshl_add_u64 v[134:135], v[128:129], 0, s[12:13]
	v_lshl_add_u64 v[136:137], v[134:135], 0, s[38:39]
	s_mov_b64 s[38:39], 0x3c8800c0
	v_mfma_f32_16x16x32_bf16 v[52:55], v[176:179], v[150:153], v[52:55]
	v_lshl_add_u64 v[134:135], v[134:135], 0, s[38:39]
	s_add_u32 s12, s12, 64
	s_addc_u32 s13, s13, 0
	v_mfma_f32_16x16x32_bf16 v[8:11], v[176:179], v[154:157], v[8:11]
	s_add_i32 s27, s27, 0x8000
	s_cmpk_eq_i32 s12, 0x1f40
	v_mfma_f32_16x16x32_bf16 v[48:51], v[176:179], v[162:165], v[48:51]
	v_mfma_f32_16x16x32_bf16 v[12:15], v[176:179], v[166:169], v[12:15]
	v_add_u32_e32 v138, 0x4000, v159
	v_add_u32_e32 v139, 0x6000, v159
	v_readfirstlane_b32 s34, v138
	v_readfirstlane_b32 s38, v139
	s_mov_b32 m0, s34
	v_mfma_f32_16x16x32_bf16 v[44:47], v[184:187], v[150:153], v[44:47]
	global_load_lds_dwordx4 v[136:137], off
	s_mov_b32 m0, s38
	v_mfma_f32_16x16x32_bf16 v[16:19], v[184:187], v[154:157], v[16:19]
	global_load_lds_dwordx4 v[134:135], off
	v_mfma_f32_16x16x32_bf16 v[40:43], v[184:187], v[162:165], v[40:43]
	v_mfma_f32_16x16x32_bf16 v[20:23], v[184:187], v[166:169], v[20:23]
	v_mfma_f32_16x16x32_bf16 v[36:39], v[192:195], v[150:153], v[36:39]
	v_mfma_f32_16x16x32_bf16 v[24:27], v[192:195], v[154:157], v[24:27]
	v_mfma_f32_16x16x32_bf16 v[32:35], v[192:195], v[162:165], v[32:35]
	v_mfma_f32_16x16x32_bf16 v[28:31], v[192:195], v[166:169], v[28:31]
	s_waitcnt lgkmcnt(0)
	v_mov_b64_e32 v[134:135], v[200:201]
	v_mov_b64_e32 v[136:137], v[202:203]
	v_mov_b64_e32 v[138:139], v[204:205]
	v_mov_b64_e32 v[140:141], v[206:207]
	v_mov_b64_e32 v[142:143], v[208:209]
	v_mov_b64_e32 v[144:145], v[210:211]
	v_mov_b64_e32 v[146:147], v[212:213]
	v_mov_b64_e32 v[148:149], v[214:215]
	v_mov_b64_e32 v[150:151], v[216:217]
	v_mov_b64_e32 v[152:153], v[218:219]
	v_mov_b64_e32 v[154:155], v[220:221]
	v_mov_b64_e32 v[156:157], v[222:223]
	v_mov_b64_e32 v[162:163], v[224:225]
	v_mov_b64_e32 v[164:165], v[226:227]
	v_mov_b64_e32 v[166:167], v[228:229]
	v_mov_b64_e32 v[168:169], v[230:231]
	s_cbranch_scc0 .LBB0_1328
	s_waitcnt vmcnt(8)
	s_barrier
; #define ROW4(accv, r, av)                                                                              \
;     accv[r][0] = MFMA16(av, b0, accv[r][0]); accv[r][1] = MFMA16(av, b1, accv[r][1]);                      \
;     accv[r][2] = MFMA16(av, b2, accv[r][2]); accv[r][3] = MFMA16(av, b3, accv[r][3]);
; template <int EPI>
; __device__ __forceinline__ void gemm_tile_dma(const bft* __restrict__ A, int lda, const bft* __restrict__ Bt, int K, int row0, int col0,
;                                               char* smem, const EpiArgs& e) {
;     ...
;   for (int kt = 0; kt < nk; ++kt) {
;     if (kt + 2 < nk) asm volatile("s_waitcnt vmcnt(8)" ::: "memory");
;     else if (kt + 1 < nk) asm volatile("s_waitcnt vmcnt(4)" ::: "memory");
;     else asm volatile("s_waitcnt vmcnt(0)" ::: "memory");
;     __builtin_amdgcn_s_barrier();
;     asm volatile("" ::: "memory");
;     const bool pf = kt + 3 < nk;
;     const unsigned so = (unsigned)(kt & 3) * GST;
;     bf16x8 a0, a1, a2, a3, b0, b1, b2, b3;
;     asm volatile(
;         "ds_read_b128 %0, %8\n\t"
;         "ds_read_b128 %1, %8 offset:1024\n\t"
;         "ds_read_b128 %2, %8 offset:2048\n\t"
;         "ds_read_b128 %3, %8 offset:3072\n\t"
;         "ds_read_b128 %4, %9\n\t"
;         "ds_read_b128 %5, %9 offset:1024\n\t"
;         "ds_read_b128 %6, %9 offset:2048\n\t"
;         "ds_read_b128 %7, %9 offset:3072\n\t"
;         "s_waitcnt lgkmcnt(0)"
;         : "=&v"(a0), "=&v"(a1), "=&v"(a2), "=&v"(a3), "=&v"(b0), "=&v"(b1), "=&v"(b2), "=&v"(b3)
;         : "v"(lds_a + so), "v"(lds_b + so)
;         : "memory");
;     ...
;     ROW4(accL, 0, a0) ROW4(accL, 1, a1)
;     if (pf) GEMM_DMA_A(kt + 3)
;     ROW4(accL, 2, a2) ROW4(accL, 3, a3)
;     asm volatile(
;         "ds_read_b128 %0, %4 offset:4096\n\t"
;         "ds_read_b128 %1, %4 offset:5120\n\t"
;         "ds_read_b128 %2, %4 offset:6144\n\t"
;         "ds_read_b128 %3, %4 offset:7168\n\t"
;         "s_waitcnt lgkmcnt(0)"
;         : "=&v"(a0), "=&v"(a1), "=&v"(a2), "=&v"(a3)
;         : "v"(lds_a + so)
;         : "memory");
;     ROW4(accH, 0, a0) ROW4(accH, 1, a1)
;     if (pf) GEMM_DMA_B(kt + 3)
;     ROW4(accH, 2, a2) ROW4(accH, 3, a3)
;     ...
;   }
	v_add_u32_e32 v158, 0x8000, v133
	v_or_b32_e32 v159, 0x8000, v132
	ds_read_b128 v[128:131], v158
	ds_read_b128 v[134:137], v158 offset:1024
	ds_read_b128 v[138:141], v158 offset:2048
	ds_read_b128 v[142:145], v158 offset:3072
	ds_read_b128 v[146:149], v159
	ds_read_b128 v[150:153], v159 offset:1024
	ds_read_b128 v[154:157], v159 offset:2048
	ds_read_b128 v[162:165], v159 offset:3072
	s_waitcnt lgkmcnt(0)
	v_or_b32_e32 v159, 0x10000, v132
	v_mfma_f32_16x16x32_bf16 v[124:127], v[128:131], v[146:149], v[124:127]
	v_add_u32_e32 v160, 0x18000, v133
	v_or_b32_e32 v132, 0x18000, v132
	s_movk_i32 s12, 0x4400
	v_mfma_f32_16x16x32_bf16 v[120:123], v[128:131], v[150:153], v[120:123]
	s_mul_i32 s13, s15, 0xf0f0f0f1
	v_and_b32_e32 v183, 63, v188
	v_mfma_f32_16x16x32_bf16 v[116:119], v[128:131], v[154:157], v[116:119]
	v_mfma_f32_16x16x32_bf16 v[108:111], v[128:131], v[162:165], v[108:111]
	v_mfma_f32_16x16x32_bf16 v[104:107], v[134:137], v[146:149], v[104:107]
	v_mfma_f32_16x16x32_bf16 v[100:103], v[134:137], v[150:153], v[100:103]
	v_mfma_f32_16x16x32_bf16 v[96:99], v[134:137], v[154:157], v[96:99]
	v_mfma_f32_16x16x32_bf16 v[92:95], v[134:137], v[162:165], v[92:95]
	v_mfma_f32_16x16x32_bf16 v[88:91], v[138:141], v[146:149], v[88:91]
	v_mfma_f32_16x16x32_bf16 v[84:87], v[138:141], v[150:153], v[84:87]
	v_mfma_f32_16x16x32_bf16 v[80:83], v[138:141], v[154:157], v[80:83]
	v_mfma_f32_16x16x32_bf16 v[76:79], v[138:141], v[162:165], v[76:79]
	v_mfma_f32_16x16x32_bf16 v[72:75], v[142:145], v[146:149], v[72:75]
	v_mfma_f32_16x16x32_bf16 v[68:71], v[142:145], v[150:153], v[68:71]
	v_mfma_f32_16x16x32_bf16 v[64:67], v[142:145], v[154:157], v[64:67]
	v_mfma_f32_16x16x32_bf16 v[60:63], v[142:145], v[162:165], v[60:63]
	ds_read_b128 v[128:131], v158 offset:4096
	ds_read_b128 v[134:137], v158 offset:5120
	ds_read_b128 v[138:141], v158 offset:6144
	ds_read_b128 v[142:145], v158 offset:7168
	s_waitcnt lgkmcnt(0)
	s_waitcnt vmcnt(4)
	s_barrier
	v_mfma_f32_16x16x32_bf16 v[112:115], v[128:131], v[146:149], v[112:115]
	v_add_u32_e32 v158, 0x10000, v133
	v_mfma_f32_16x16x32_bf16 v[0:3], v[128:131], v[150:153], v[0:3]
	v_mfma_f32_16x16x32_bf16 v[56:59], v[128:131], v[154:157], v[56:59]
	v_mfma_f32_16x16x32_bf16 v[4:7], v[128:131], v[162:165], v[4:7]
	v_mfma_f32_16x16x32_bf16 v[52:55], v[134:137], v[146:149], v[52:55]
	v_mfma_f32_16x16x32_bf16 v[8:11], v[134:137], v[150:153], v[8:11]
	v_mfma_f32_16x16x32_bf16 v[48:51], v[134:137], v[154:157], v[48:51]
	v_mfma_f32_16x16x32_bf16 v[12:15], v[134:137], v[162:165], v[12:15]
	v_mfma_f32_16x16x32_bf16 v[44:47], v[138:141], v[146:149], v[44:47]
	v_mfma_f32_16x16x32_bf16 v[16:19], v[138:141], v[150:153], v[16:19]
	v_mfma_f32_16x16x32_bf16 v[128:131], v[138:141], v[154:157], v[40:43]
	v_mfma_f32_16x16x32_bf16 v[20:23], v[138:141], v[162:165], v[20:23]
	v_mfma_f32_16x16x32_bf16 v[134:137], v[142:145], v[146:149], v[36:39]
	v_mfma_f32_16x16x32_bf16 v[24:27], v[142:145], v[150:153], v[24:27]
	v_mfma_f32_16x16x32_bf16 v[32:35], v[142:145], v[154:157], v[32:35]
	v_mfma_f32_16x16x32_bf16 v[28:31], v[142:145], v[162:165], v[28:31]
	ds_read_b128 v[138:141], v158
	ds_read_b128 v[142:145], v158 offset:1024
	ds_read_b128 v[146:149], v158 offset:2048
	ds_read_b128 v[150:153], v158 offset:3072
	ds_read_b128 v[154:157], v159
	ds_read_b128 v[40:43], v159 offset:1024
	ds_read_b128 v[162:165], v159 offset:2048
	ds_read_b128 v[36:39], v159 offset:3072
	s_waitcnt lgkmcnt(0)
	s_nop 0
	v_mfma_f32_16x16x32_bf16 v[124:127], v[138:141], v[154:157], v[124:127]
	v_mfma_f32_16x16x32_bf16 v[120:123], v[138:141], v[40:43], v[120:123]
	v_mfma_f32_16x16x32_bf16 v[116:119], v[138:141], v[162:165], v[116:119]
	v_mfma_f32_16x16x32_bf16 v[108:111], v[138:141], v[36:39], v[108:111]
	v_mfma_f32_16x16x32_bf16 v[104:107], v[142:145], v[154:157], v[104:107]
	v_mfma_f32_16x16x32_bf16 v[100:103], v[142:145], v[40:43], v[100:103]
	v_mfma_f32_16x16x32_bf16 v[96:99], v[142:145], v[162:165], v[96:99]
	v_mfma_f32_16x16x32_bf16 v[138:141], v[142:145], v[36:39], v[92:95]
	v_mfma_f32_16x16x32_bf16 v[142:145], v[146:149], v[154:157], v[88:91]
	v_mfma_f32_16x16x32_bf16 v[178:181], v[146:149], v[40:43], v[84:87]
	v_mfma_f32_16x16x32_bf16 v[184:187], v[146:149], v[162:165], v[80:83]
	v_mfma_f32_16x16x32_bf16 v[76:79], v[146:149], v[36:39], v[76:79]
	v_mfma_f32_16x16x32_bf16 v[192:195], v[150:153], v[154:157], v[72:75]
	v_mfma_f32_16x16x32_bf16 v[198:201], v[150:153], v[40:43], v[68:71]
	v_mfma_f32_16x16x32_bf16 v[206:209], v[150:153], v[36:39], v[60:63]
	ds_read_b128 v[88:91], v158 offset:4096
	ds_read_b128 v[84:87], v158 offset:5120
	ds_read_b128 v[68:71], v158 offset:6144
	ds_read_b128 v[60:63], v158 offset:7168
	s_waitcnt lgkmcnt(0)
	s_waitcnt vmcnt(0)
	s_barrier
	v_mfma_f32_16x16x32_bf16 v[210:213], v[88:91], v[154:157], v[112:115]
	v_mfma_f32_16x16x32_bf16 v[202:205], v[150:153], v[162:165], v[64:67]
	v_mfma_f32_16x16x32_bf16 v[64:67], v[88:91], v[162:165], v[56:59]
	v_mfma_f32_16x16x32_bf16 v[214:217], v[84:87], v[154:157], v[52:55]
	v_mfma_f32_16x16x32_bf16 v[72:75], v[84:87], v[162:165], v[48:51]
	v_mfma_f32_16x16x32_bf16 v[80:83], v[68:71], v[162:165], v[128:131]
	v_mfma_f32_16x16x32_bf16 v[56:59], v[60:63], v[162:165], v[32:35]
	ds_read_b128 v[32:35], v160
	ds_read_b128 v[112:115], v160 offset:1024
	ds_read_b128 v[128:131], v160 offset:2048
	ds_read_b128 v[222:225], v160 offset:3072
	ds_read_b128 v[226:229], v132
	ds_read_b128 v[52:55], v132 offset:1024
	ds_read_b128 v[92:95], v132 offset:2048
	ds_read_b128 v[48:51], v132 offset:3072
	s_waitcnt lgkmcnt(0)
	s_nop 0
	v_mfma_f32_16x16x32_bf16 v[148:151], v[112:115], v[48:51], v[138:141]
	v_mfma_f32_16x16x32_bf16 v[144:147], v[128:131], v[226:229], v[142:145]
	v_mfma_f32_16x16x32_bf16 v[140:143], v[128:131], v[52:55], v[178:181]
	s_nop 2
	v_lshrrev_b32_e32 v178, 6, v188
	v_mfma_f32_16x16x32_bf16 v[44:47], v[68:71], v[154:157], v[44:47]
	v_mfma_f32_16x16x32_bf16 v[218:221], v[60:63], v[154:157], v[134:137]
	v_mfma_f32_16x16x32_bf16 v[166:169], v[32:35], v[48:51], v[108:111]
	v_mfma_f32_16x16x32_bf16 v[162:165], v[112:115], v[226:229], v[104:107]
	v_mfma_f32_16x16x32_bf16 v[156:159], v[112:115], v[52:55], v[100:103]
	v_mfma_f32_16x16x32_bf16 v[152:155], v[112:115], v[92:95], v[96:99]
	ds_read_b128 v[112:115], v160 offset:4096
	ds_read_b128 v[108:111], v160 offset:5120
	ds_read_b128 v[104:107], v160 offset:6144
	ds_read_b128 v[100:103], v160 offset:7168
	s_waitcnt lgkmcnt(0)
	v_and_b32_e32 v160, 0xc0, v188
	s_waitcnt vmcnt(0) lgkmcnt(0)
	v_mfma_f32_16x16x32_bf16 v[136:139], v[128:131], v[92:95], v[184:187]
	s_barrier
; template <int EPI>
; DI void epilogue_tile(const EpiArgs& e, int row0, int wrow, int wcol, f32x4 (&acc)[4][4], char* smem, const float* rsm, int wave, int lane,
;                       bool final_sync = true) {
;     ...
;   const int b = row0 / NTOK, n0 = wrow - b * NTOK;
;   const int mi_mod = (row0 % NTOK) < CTXL ? 16 : b;
;   bool transposed = false;
;   if constexpr (EPI == EPI_IN) transposed = wcol >= 1280;
;   if constexpr (EPI == EPI_KV) transposed = (wcol & 64) != 0;
; #pragma unroll
;   for (int mi = 0; mi < 4; ++mi)
; #pragma unroll
;     for (int ni = 0; ni < 4; ++ni) {
;       const int lrow = mi * 16 + 4 * g, lcol = ni * 16 + r16;
;       const int col = wcol + lcol;
;       float v[4];
; #pragma unroll
;       for (int j = 0; j < 4; ++j) v[j] = acc[mi][ni][j];
;       if constexpr (EPI == EPI_Q || EPI == EPI_KV) {
; #pragma unroll
;         for (int j = 0; j < 4; ++j) v[j] *= rsm[lrow + j];
;       }
;       if constexpr (EPI == EPI_Q) {
;         const int d = col % 96;
;         if (d >= 64) {
;           const int i = d & 7;
;           const bool second = (d & 8) != 0;
;           const bool colrope = d >= 80;
;           const float inv = exp2f(-(float)i * (13.287712379549449f / 8.f));
; #pragma unroll
;           for (int j = 0; j < 4; ++j) {
;             const float partner = __shfl_xor(v[j], 8);
;             const int nn = n0 + lrow + j;
;             float cs = 1.f, sn = 0.f;
;             if (nn >= CTXL) {
;               const int t = nn - CTXL;
;               const float pos = (float)(colrope ? (t & 63) : (t >> 6));
;               { const float a_ = pos * inv; sn = __sinf(a_); cs = __cosf(a_); }
;             }
;             v[j] = second ? (v[j] * cs + partner * sn) : (v[j] * cs - partner * sn);
;           }
;         }
;       }
;       if constexpr (EPI == EPI_RES) {
;         const float gg = e.gate[(size_t)mi_mod * 6144 + col], bb = e.bias[col];
; #pragma unroll
;         for (int j = 0; j < 4; ++j) v[j] = gg * (v[j] + bb);
;       }
;       if constexpr (EPI == EPI_FF1) {
;         const float bb = e.bias[col];
; #pragma unroll
;         for (int j = 0; j < 4; ++j) { const float t = fmaxf(v[j] + bb, 0.f); v[j] = t * t; }
;       }
;       if (transposed) {
;         *(f32x4*)(stage + lcol * STG + lrow) = (f32x4){v[0], v[1], v[2], v[3]};
;       } else {
; #pragma unroll
	v_mfma_f32_16x16x32_bf16 v[132:135], v[128:131], v[48:51], v[76:79]
	v_mfma_f32_16x16x32_bf16 v[128:131], v[222:225], v[226:229], v[192:195]
	s_nop 2
	v_mul_lo_u32 v195, v178, s12
	s_mul_hi_u32 s12, s16, 0xf0f0f10
	v_mfma_f32_16x16x32_bf16 v[96:99], v[112:115], v[226:229], v[210:213]
	s_mulk_i32 s12, 0x6000
	v_mov_b32_e32 v178, 0x60000
	v_lshl_or_b32 v192, v182, 2, v195
	v_or_b32_e32 v211, s17, v160
	v_alignbit_b32 v160, s13, s13, 8
	s_mov_b32 s13, 0xf0f0f
	v_cmp_lt_u32_e32 vcc, s13, v160
	v_mov_b32_e32 v160, s12
	v_mfma_f32_16x16x32_bf16 v[76:79], v[108:111], v[226:229], v[214:217]
	v_cndmask_b32_e32 v160, v178, v160, vcc
	v_lshl_add_u64 v[186:187], s[10:11], 0, v[160:161]
	v_or_b32_e32 v160, v211, v182
	v_lshlrev_b32_e32 v160, 2, v160
	v_readfirstlane_b32 s12, v186
	v_readfirstlane_b32 s13, v187
	global_load_dword v215, v160, s[6:7]
	v_mfma_f32_16x16x32_bf16 v[230:233], v[32:35], v[226:229], v[124:127]
	v_bfe_u32 v212, v188, 2, 4
	v_lshl_add_u64 v[178:179], v[186:187], 0, v[160:161]
	v_lshl_add_u64 v[180:181], s[6:7], 0, v[160:161]
	global_load_dword v214, v160, s[12:13]
	v_mfma_f32_16x16x32_bf16 v[124:127], v[222:225], v[52:55], v[198:201]
	s_waitcnt vmcnt(1)
	s_nop 1
	v_add_f32_e32 v160, v230, v215
	v_and_b32_e32 v198, 12, v212
	v_or_b32_e32 v199, 48, v183
	v_add_f32_e32 v183, v231, v215
	v_add_f32_e32 v184, v232, v215
	s_waitcnt vmcnt(0)
	v_mul_f32_e32 v160, v214, v160
	v_mad_u32_u24 v213, v198, s35, v192
	v_mul_f32_e32 v183, v214, v183
	v_mul_f32_e32 v184, v214, v184
	ds_write_b32 v213, v160
	ds_write_b32 v213, v183 offset:272
	ds_write_b32 v213, v184 offset:544
	v_add_lshl_u32 v160, v211, v182, 2
	global_load_dword v216, v160, s[12:13] offset:64
	global_load_dword v217, v160, s[6:7] offset:64
	v_mfma_f32_16x16x32_bf16 v[174:177], v[32:35], v[52:55], v[120:123]
	v_add_f32_e32 v185, v233, v215
	v_or_b32_e32 v200, 3, v212
	v_mul_f32_e32 v185, v214, v185
	v_mad_u32_u24 v201, v200, s35, v192
	ds_write_b32 v201, v185
	v_mfma_f32_16x16x32_bf16 v[170:173], v[32:35], v[92:95], v[116:119]
	v_lshl_add_u64 v[182:183], v[186:187], 0, v[160:161]
	v_lshl_add_u64 v[184:185], s[6:7], 0, v[160:161]
	v_lshl_or_b32 v191, v199, 2, v195
	v_add_f32_e32 v162, v162, v215
	v_add_f32_e32 v163, v163, v215
	v_mul_f32_e32 v162, v214, v162
	v_mul_f32_e32 v163, v214, v163
	v_add_f32_e32 v164, v164, v215
	v_mul_f32_e32 v164, v214, v164
	v_add_f32_e32 v165, v165, v215
	v_mul_f32_e32 v165, v214, v165
	v_add_f32_e32 v144, v144, v215
	v_add_f32_e32 v145, v145, v215
	v_mul_f32_e32 v144, v214, v144
	v_mul_f32_e32 v145, v214, v145
	v_add_f32_e32 v146, v146, v215
	v_mfma_f32_16x16x32_bf16 v[120:123], v[222:225], v[92:95], v[202:205]
	v_mul_f32_e32 v146, v214, v146
	v_add_f32_e32 v147, v147, v215
	v_mul_f32_e32 v147, v214, v147
	v_mfma_f32_16x16x32_bf16 v[116:119], v[222:225], v[48:51], v[206:209]
	v_add_f32_e32 v128, v128, v215
	v_add_f32_e32 v129, v129, v215
	v_mul_f32_e32 v128, v214, v128
	v_mul_f32_e32 v129, v214, v129
	v_add_f32_e32 v130, v130, v215
	v_mul_f32_e32 v130, v214, v130
	v_add_f32_e32 v131, v131, v215
	v_mul_f32_e32 v131, v214, v131
	v_mfma_f32_16x16x32_bf16 v[44:47], v[104:107], v[226:229], v[44:47]
	v_mul_u32_u24_e32 v193, 0x110, v198
	v_mul_u32_u24_e32 v194, 0x110, v200
	s_waitcnt vmcnt(0)
	v_add_f32_e32 v174, v174, v217
	v_mul_f32_e32 v174, v216, v174
	v_add_f32_e32 v175, v175, v217
	v_add_f32_e32 v176, v176, v217
	v_add_f32_e32 v177, v177, v217
	v_mul_f32_e32 v175, v216, v175
	v_mul_f32_e32 v176, v216, v176
	v_mul_f32_e32 v177, v216, v177
	ds_write_b32 v213, v174 offset:64
	ds_write_b32 v213, v175 offset:336
	ds_write_b32 v213, v176 offset:608
	ds_write_b32 v201, v177 offset:64
	global_load_dword v174, v160, s[12:13] offset:128
	global_load_dword v175, v160, s[6:7] offset:128
	v_mad_u32_u24 v177, v198, s35, v191
	v_add_f32_e32 v156, v156, v217
	v_mul_f32_e32 v156, v216, v156
	v_add_f32_e32 v157, v157, v217
	v_add_f32_e32 v158, v158, v217
	v_add_f32_e32 v159, v159, v217
	v_mul_f32_e32 v157, v216, v157
	v_mul_f32_e32 v158, v216, v158
	v_mul_f32_e32 v159, v216, v159
	v_add_f32_e32 v140, v140, v217
	v_mul_f32_e32 v140, v216, v140
	v_add_f32_e32 v141, v141, v217
	v_add_f32_e32 v142, v142, v217
	v_add_f32_e32 v143, v143, v217
	v_mul_f32_e32 v141, v216, v141
	v_mul_f32_e32 v142, v216, v142
	v_mul_f32_e32 v143, v216, v143
	v_add_f32_e32 v124, v124, v217
	v_mul_f32_e32 v124, v216, v124
	v_add_f32_e32 v125, v125, v217
	v_add_f32_e32 v126, v126, v217
	v_add_f32_e32 v127, v127, v217
	v_mul_f32_e32 v125, v216, v125
	v_mul_f32_e32 v126, v216, v126
	v_mul_f32_e32 v127, v216, v127
	v_mfma_f32_16x16x32_bf16 v[32:35], v[100:103], v[226:229], v[218:221]
	s_waitcnt vmcnt(0)
; template <int EPI>
; DI void epilogue_tile(const EpiArgs& e, int row0, int wrow, int wcol, f32x4 (&acc)[4][4], char* smem, const float* rsm, int wave, int lane,
;                       bool final_sync = true) {
;     ...
;       if constexpr (EPI == EPI_RES) {
;         const float gg = e.gate[(size_t)mi_mod * 6144 + col], bb = e.bias[col];
; #pragma unroll
;         for (int j = 0; j < 4; ++j) v[j] = gg * (v[j] + bb);
;       }
;       if constexpr (EPI == EPI_FF1) {
;         const float bb = e.bias[col];
; #pragma unroll
;         for (int j = 0; j < 4; ++j) { const float t = fmaxf(v[j] + bb, 0.f); v[j] = t * t; }
;       }
;       if (transposed) {
;         *(f32x4*)(stage + lcol * STG + lrow) = (f32x4){v[0], v[1], v[2], v[3]};
;       } else {
; #pragma unroll
;         for (int j = 0; j < 4; ++j) stage[(lrow + j) * STG + lcol] = v[j];
;       }
;     }
;   const int rr = lane >> 3, c8 = (lane & 7) * 8;
; #pragma unroll 4
;   for (int it = 0; it < 8; ++it) {
;     const int sr = it * 8 + rr;
;     const f32x4 v0 = *(const f32x4*)(stage + sr * STG + c8);
;     const f32x4 v1 = *(const f32x4*)(stage + sr * STG + c8 + 4);
;     if constexpr (EPI == EPI_RES) {
;       bft* px = (bft*)(e.ws + OFF_XS) + (size_t)(wrow + sr) * D + wcol + c8;
	v_add_f32_e32 v160, v170, v175
	v_mul_f32_e32 v160, v174, v160
	v_add_f32_e32 v170, v171, v175
	v_add_f32_e32 v171, v172, v175
	v_add_f32_e32 v172, v173, v175
	v_mul_f32_e32 v170, v174, v170
	v_mul_f32_e32 v171, v174, v171
	v_mul_f32_e32 v172, v174, v172
	ds_write_b32 v213, v160 offset:128
	ds_write_b32 v213, v170 offset:400
	ds_write_b32 v213, v171 offset:672
	ds_write_b32 v201, v172 offset:128
	v_or_b32_e32 v160, v211, v199
	v_lshlrev_b32_e32 v160, 2, v160
	v_lshl_add_u64 v[170:171], v[186:187], 0, v[160:161]
	global_load_dword v176, v160, s[12:13]
	v_lshl_add_u64 v[172:173], s[6:7], 0, v[160:161]
	global_load_dword v160, v160, s[6:7]
	v_add_f32_e32 v152, v152, v175
	v_mul_f32_e32 v152, v174, v152
	v_add_f32_e32 v153, v153, v175
	v_add_f32_e32 v154, v154, v175
	v_add_f32_e32 v155, v155, v175
	v_mul_f32_e32 v153, v174, v153
	v_mul_f32_e32 v154, v174, v154
	v_mul_f32_e32 v155, v174, v155
	v_add_f32_e32 v136, v136, v175
	v_mul_f32_e32 v136, v174, v136
	v_add_f32_e32 v137, v137, v175
	v_add_f32_e32 v138, v138, v175
	v_add_f32_e32 v139, v139, v175
	v_mul_f32_e32 v137, v174, v137
	v_mul_f32_e32 v138, v174, v138
	v_mul_f32_e32 v139, v174, v139
	v_add_f32_e32 v120, v120, v175
	v_mul_f32_e32 v120, v174, v120
	v_add_f32_e32 v121, v121, v175
	v_add_f32_e32 v122, v122, v175
	v_add_f32_e32 v123, v123, v175
	v_mul_f32_e32 v121, v174, v121
	v_mul_f32_e32 v122, v174, v122
	v_mul_f32_e32 v123, v174, v123
	s_mov_b32 s12, 0
	s_waitcnt vmcnt(0)
	v_add_f32_e32 v166, v166, v160
	v_add_f32_e32 v167, v167, v160
	v_mul_f32_e32 v166, v176, v166
	v_mul_f32_e32 v167, v176, v167
	v_add_f32_e32 v168, v168, v160
	v_add_f32_e32 v169, v169, v160
	v_mul_f32_e32 v168, v176, v168
	v_mul_f32_e32 v169, v176, v169
	ds_write2_b32 v177, v166, v167 offset1:68
	ds_write_b32 v177, v168 offset:544
	v_mad_u32_u24 v166, v200, s35, v191
	ds_write_b32 v166, v169
	ds_write_b32 v213, v162 offset:4352
	ds_write_b32 v213, v163 offset:4624
	ds_write_b32 v213, v164 offset:4896
	v_or_b32_e32 v163, 19, v212
	v_mad_u32_u24 v164, v163, s35, v192
	v_add_f32_e32 v148, v148, v160
	v_add_f32_e32 v149, v149, v160
	ds_write_b32 v164, v165
	ds_write_b32 v213, v156 offset:4416
	ds_write_b32 v213, v157 offset:4688
	ds_write_b32 v213, v158 offset:4960
	ds_write_b32 v164, v159 offset:64
	ds_write_b32 v213, v152 offset:4480
	ds_write_b32 v213, v153 offset:4752
	ds_write_b32 v213, v154 offset:5024
	ds_write_b32 v164, v155 offset:128
	v_mul_f32_e32 v148, v176, v148
	v_mul_f32_e32 v149, v176, v149
	v_add_f32_e32 v150, v150, v160
	v_add_f32_e32 v151, v151, v160
	v_add_u32_e32 v152, 0x1000, v177
	v_mul_f32_e32 v150, v176, v150
	v_mul_f32_e32 v151, v176, v151
	ds_write2_b32 v152, v148, v149 offset0:64 offset1:132
	ds_write_b32 v177, v150 offset:4896
	v_mad_u32_u24 v148, v163, s35, v191
	ds_write_b32 v148, v151
	ds_write_b32 v213, v144 offset:8704
	ds_write_b32 v213, v145 offset:8976
	ds_write_b32 v213, v146 offset:9248
	v_or_b32_e32 v145, 35, v212
	v_mad_u32_u24 v146, v145, s35, v192
	v_add_f32_e32 v132, v132, v160
	v_add_f32_e32 v133, v133, v160
	ds_write_b32 v146, v147
	ds_write_b32 v213, v140 offset:8768
	ds_write_b32 v213, v141 offset:9040
	ds_write_b32 v213, v142 offset:9312
	ds_write_b32 v146, v143 offset:64
	ds_write_b32 v213, v136 offset:8832
	ds_write_b32 v213, v137 offset:9104
	ds_write_b32 v213, v138 offset:9376
	ds_write_b32 v146, v139 offset:128
	v_mul_f32_e32 v132, v176, v132
	v_mul_f32_e32 v133, v176, v133
	v_add_f32_e32 v134, v134, v160
	v_add_f32_e32 v135, v135, v160
	v_add_u32_e32 v136, 0x2000, v177
	v_mul_f32_e32 v134, v176, v134
	v_mul_f32_e32 v135, v176, v135
	ds_write2_b32 v136, v132, v133 offset0:128 offset1:196
	ds_write_b32 v177, v134 offset:9248
	v_mad_u32_u24 v132, v145, s35, v191
	ds_write_b32 v132, v135
	ds_write_b32 v213, v128 offset:13056
	ds_write_b32 v213, v129 offset:13328
	ds_write_b32 v213, v130 offset:13600
	v_or_b32_e32 v129, 51, v212
	v_mad_u32_u24 v130, v129, s35, v192
	v_add_f32_e32 v116, v116, v160
	v_add_f32_e32 v117, v117, v160
	ds_write_b32 v130, v131
	ds_write_b32 v213, v124 offset:13120
	ds_write_b32 v213, v125 offset:13392
	ds_write_b32 v213, v126 offset:13664
	ds_write_b32 v130, v127 offset:64
	ds_write_b32 v213, v120 offset:13184
	ds_write_b32 v213, v121 offset:13456
	ds_write_b32 v213, v122 offset:13728
	ds_write_b32 v130, v123 offset:128
	v_mul_f32_e32 v116, v176, v116
	v_mul_f32_e32 v117, v176, v117
	v_add_f32_e32 v118, v118, v160
	v_add_f32_e32 v119, v119, v160
	v_add_u32_e32 v120, 0x3200, v177
	v_mul_f32_e32 v118, v176, v118
	v_mul_f32_e32 v119, v176, v119
	ds_write2_b32 v120, v116, v117 offset0:64 offset1:132
	ds_write_b32 v177, v118 offset:13600
	v_mad_u32_u24 v116, v129, s35, v191
	ds_write_b32 v116, v119
	v_bfe_u32 v118, v188, 3, 3
	v_and_b32_e32 v119, 7, v188
	v_lshlrev_b32_e32 v160, 1, v211
	v_add3_u32 v120, v118, s15, v189
	v_mul_u32_u24_e32 v118, 0x110, v118
	v_lshlrev_b32_e32 v119, 5, v119
	v_lshl_add_u64 v[116:117], s[90:91], 0, v[160:161]
	v_and_b32_e32 v160, 0x70, v190
	v_add3_u32 v121, v195, v118, v119
	v_mul_u32_u24_e32 v162, 0x110, v163
	v_mul_u32_u24_e32 v144, 0x110, v145
	v_mul_u32_u24_e32 v128, 0x110, v129
	v_lshl_add_u64 v[116:117], v[116:117], 0, v[160:161]
	v_mov_b32_e32 v122, v121
